# P0 XN (normalized activations, bf16) stores nt
# baseline (speedup 1.0000x reference)
; #define P0_LOADROW(buf, mm) do { const int m_ = (mm); if (m_ < M) { const float* xr_ = m_ < MP ? P.x_p + (size_t)m_ * 1024 : P.x_s + (size_t)(m_ - MP) * 1024; \
;         _Pragma("unroll") for (int j = 0; j < 4; ++j) buf[j] = ((const f32x4*)xr_)[64 * j + lane]; } } while (0)
; __device__ __forceinline__ void phase0(const Params& P, LAS unsigned char* lds, int tid, int lane, int wave, int G) {
;     ...
;     P0_LOADROW(rb0, gw); P0_LOADROW(rb1, gw + NGW); P0_LOADROW(rb2, gw + 2 * NGW);
;     for (int m = gw; m < M; m += 3 * NGW) {
;         P0_DOROW(rb0, m);           P0_LOADROW(rb0, m + 3 * NGW);
;         P0_DOROW(rb1, m + NGW);     P0_LOADROW(rb1, m + 4 * NGW);
;         P0_DOROW(rb2, m + 2 * NGW); P0_LOADROW(rb2, m + 5 * NGW);
.LBB0_54:
	s_waitcnt vmcnt(3)
	v_pk_mul_f32 v[84:85], v[20:21], v[20:21]
	v_pk_mul_f32 v[86:87], v[18:19], v[18:19]
	s_waitcnt vmcnt(2)
	v_pk_mul_f32 v[80:81], v[24:25], v[24:25]
	v_pk_mul_f32 v[82:83], v[22:23], v[22:23]
	v_pk_mov_b32 v[88:89], v[86:87], v[84:85] op_sel:[1,0]
	v_mov_b32_e32 v87, v85
	v_pk_add_f32 v[84:85], v[88:89], v[86:87]
	v_pk_mov_b32 v[86:87], v[82:83], v[80:81] op_sel:[1,0]
	v_mov_b32_e32 v83, v81
	v_pk_add_f32 v[80:81], v[86:87], v[82:83]
	v_pk_add_f32 v[84:85], v[84:85], v[84:85] op_sel_hi:[0,1]
	v_pk_add_f32 v[80:81], v[80:81], v[80:81] op_sel_hi:[0,1]
	s_waitcnt vmcnt(1)
	v_mul_f32_e32 v80, v26, v26
	v_pk_fma_f32 v[82:83], v[26:27], v[26:27], v[80:81] op_sel_hi:[1,1,0]
	v_mul_f32_e32 v80, v28, v28
	v_pk_fma_f32 v[86:87], v[28:29], v[28:29], v[80:81] op_sel_hi:[1,1,0]
	s_waitcnt vmcnt(0)
	v_mul_f32_e32 v82, v30, v30
	v_mul_f32_e32 v86, v31, v31
	v_mul_f32_e32 v84, v32, v32
	v_mul_f32_e32 v80, v33, v33
	v_pk_add_f32 v[82:83], v[82:83], v[86:87]
	v_pk_add_f32 v[80:81], v[84:85], v[80:81]
	s_add_i32 s7, s30, s34
	v_pk_add_f32 v[80:81], v[82:83], v[80:81]
	s_cmp_lt_i32 s7, 0x10100
	v_add_f32_e32 v79, v80, v81
	ds_bpermute_b32 v80, v67, v79
	s_waitcnt lgkmcnt(0)
	v_add_f32_e32 v79, v79, v80
	ds_bpermute_b32 v80, v74, v79
	s_waitcnt lgkmcnt(0)
	v_add_f32_e32 v79, v79, v80
	ds_bpermute_b32 v80, v75, v79
	s_waitcnt lgkmcnt(0)
	v_add_f32_e32 v79, v79, v80
	ds_bpermute_b32 v80, v76, v79
	s_waitcnt lgkmcnt(0)
	v_add_f32_e32 v79, v79, v80
	ds_bpermute_b32 v80, v77, v79
	s_waitcnt lgkmcnt(0)
	v_add_f32_e32 v79, v79, v80
	ds_bpermute_b32 v80, v78, v79
	s_waitcnt lgkmcnt(0)
	v_add_f32_e32 v79, v79, v80
	v_fmamk_f32 v79, v79, 0x3a800000, v69
	v_rsq_f32_e32 v80, v79
	s_nop 0
	v_pk_mul_f32 v[82:83], v[18:19], v[80:81] op_sel_hi:[1,0]
	v_pk_mul_f32 v[84:85], v[20:21], v[80:81] op_sel_hi:[1,0]
	v_pk_mul_f32 v[86:87], v[22:23], v[80:81] op_sel_hi:[1,0]
	v_pk_mul_f32 v[88:89], v[24:25], v[80:81] op_sel_hi:[1,0]
	v_pk_mul_f32 v[84:85], v[4:5], v[84:85]
	v_pk_mul_f32 v[82:83], v[2:3], v[82:83]
	v_pk_mul_f32 v[88:89], v[8:9], v[88:89]
	v_pk_mul_f32 v[86:87], v[6:7], v[86:87]
	v_cvt_pk_bf16_f32 v82, v82, v83
	v_cvt_pk_bf16_f32 v83, v84, v85
	v_pk_mul_f32 v[90:91], v[26:27], v[80:81] op_sel_hi:[1,0]
	v_cvt_pk_bf16_f32 v84, v86, v87
	v_cvt_pk_bf16_f32 v85, v88, v89
	global_store_dwordx2 v[72:73], v[82:83], off nt
	global_store_dwordx2 v[72:73], v[84:85], off offset:512 nt
	v_pk_mul_f32 v[82:83], v[28:29], v[80:81] op_sel_hi:[1,0]
	v_pk_mul_f32 v[84:85], v[10:11], v[90:91]
	v_pk_mul_f32 v[82:83], v[12:13], v[82:83]
	v_cvt_pk_bf16_f32 v84, v84, v85
	v_cvt_pk_bf16_f32 v85, v82, v83
	v_pk_mul_f32 v[82:83], v[30:31], v[80:81] op_sel_hi:[1,0]
	v_pk_mul_f32 v[80:81], v[32:33], v[80:81] op_sel_hi:[1,0]
	v_pk_mul_f32 v[82:83], v[14:15], v[82:83]
	v_pk_mul_f32 v[80:81], v[16:17], v[80:81]
	v_cvt_pk_bf16_f32 v82, v82, v83
	v_cvt_pk_bf16_f32 v83, v80, v81
	global_store_dwordx2 v[72:73], v[84:85], off offset:1024 nt
	global_store_dwordx2 v[72:73], v[82:83], off offset:1536 nt
	s_cbranch_scc0 .LBB0_59
	s_add_i32 s10, s7, 0xffff0000
	s_cmp_lt_i32 s7, 0x10000
	s_cselect_b32 s11, s35, 0
	s_cselect_b32 s10, s31, s10
	s_cselect_b32 s7, s69, s71
	s_cselect_b32 s12, s68, s70
	s_lshl_b64 s[10:11], s[10:11], 12
	s_add_u32 s10, s12, s10
	s_addc_u32 s11, s7, s11
	global_load_dwordx4 v[18:21], v1, s[10:11] nt
	global_load_dwordx4 v[22:25], v1, s[10:11] offset:1024 nt
	global_load_dwordx4 v[26:29], v1, s[10:11] offset:2048 nt
	global_load_dwordx4 v[30:33], v1, s[10:11] offset:3072 nt
	s_add_i32 s10, s26, s34
	s_cmp_gt_i32 s10, 0x100ff
	s_cbranch_scc0 .LBB0_60

.LBB0_60:
	v_pk_mul_f32 v[80:81], v[36:37], v[36:37]
	v_pk_mul_f32 v[82:83], v[34:35], v[34:35]
	s_ashr_i32 s11, s10, 31
	v_pk_mov_b32 v[84:85], v[82:83], v[80:81] op_sel:[1,0]
	v_mov_b32_e32 v83, v81
	v_pk_add_f32 v[80:81], v[84:85], v[82:83]
	v_pk_mul_f32 v[82:83], v[40:41], v[40:41]
	v_pk_add_f32 v[80:81], v[80:81], v[80:81] op_sel_hi:[0,1]
	v_pk_mul_f32 v[84:85], v[38:39], v[38:39]
	v_mul_f32_e32 v80, v42, v42
	v_pk_mov_b32 v[86:87], v[84:85], v[82:83] op_sel:[1,0]
	v_mov_b32_e32 v85, v83
	v_pk_add_f32 v[82:83], v[86:87], v[84:85]
	v_pk_fma_f32 v[84:85], v[42:43], v[42:43], v[80:81] op_sel_hi:[1,1,0]
	v_mul_f32_e32 v80, v44, v44
	v_pk_add_f32 v[82:83], v[82:83], v[82:83] op_sel_hi:[0,1]
	v_pk_fma_f32 v[86:87], v[44:45], v[44:45], v[80:81] op_sel_hi:[1,1,0]
	v_mul_f32_e32 v84, v46, v46
	v_mul_f32_e32 v86, v47, v47
	v_mul_f32_e32 v82, v48, v48
	v_mul_f32_e32 v80, v49, v49
	v_pk_add_f32 v[84:85], v[84:85], v[86:87]
	v_pk_add_f32 v[80:81], v[82:83], v[80:81]
	s_lshl_b64 s[10:11], s[10:11], 11
	v_pk_add_f32 v[80:81], v[84:85], v[80:81]
	v_lshl_add_u64 v[82:83], v[70:71], 0, s[10:11]
	v_add_f32_e32 v79, v80, v81
	ds_bpermute_b32 v80, v67, v79
	s_waitcnt lgkmcnt(0)
	v_add_f32_e32 v79, v79, v80
	ds_bpermute_b32 v80, v74, v79
	s_waitcnt lgkmcnt(0)
	v_add_f32_e32 v79, v79, v80
	ds_bpermute_b32 v80, v75, v79
	s_waitcnt lgkmcnt(0)
	v_add_f32_e32 v79, v79, v80
	ds_bpermute_b32 v80, v76, v79
	s_waitcnt lgkmcnt(0)
	v_add_f32_e32 v79, v79, v80
	ds_bpermute_b32 v80, v77, v79
	s_waitcnt lgkmcnt(0)
	v_add_f32_e32 v79, v79, v80
	ds_bpermute_b32 v80, v78, v79
	s_waitcnt lgkmcnt(0)
	v_add_f32_e32 v79, v79, v80
	v_fmamk_f32 v79, v79, 0x3a800000, v69
	v_rsq_f32_e32 v80, v79
	s_nop 0
	v_pk_mul_f32 v[84:85], v[34:35], v[80:81] op_sel_hi:[1,0]
	v_pk_mul_f32 v[86:87], v[36:37], v[80:81] op_sel_hi:[1,0]
	v_pk_mul_f32 v[88:89], v[38:39], v[80:81] op_sel_hi:[1,0]
	v_pk_mul_f32 v[90:91], v[40:41], v[80:81] op_sel_hi:[1,0]
	v_pk_mul_f32 v[86:87], v[4:5], v[86:87]
	v_pk_mul_f32 v[84:85], v[2:3], v[84:85]
	v_pk_mul_f32 v[90:91], v[8:9], v[90:91]
	v_pk_mul_f32 v[88:89], v[6:7], v[88:89]
	v_cvt_pk_bf16_f32 v84, v84, v85
	v_cvt_pk_bf16_f32 v85, v86, v87
	v_cvt_pk_bf16_f32 v86, v88, v89
	v_cvt_pk_bf16_f32 v87, v90, v91
	global_store_dwordx2 v[82:83], v[84:85], off nt
	global_store_dwordx2 v[82:83], v[86:87], off offset:512 nt
	v_pk_mul_f32 v[84:85], v[42:43], v[80:81] op_sel_hi:[1,0]
	v_pk_mul_f32 v[86:87], v[44:45], v[80:81] op_sel_hi:[1,0]
	v_pk_mul_f32 v[84:85], v[10:11], v[84:85]
	v_pk_mul_f32 v[86:87], v[12:13], v[86:87]
	v_cvt_pk_bf16_f32 v84, v84, v85
	v_cvt_pk_bf16_f32 v85, v86, v87
	global_store_dwordx2 v[82:83], v[84:85], off offset:1024 nt
	v_pk_mul_f32 v[84:85], v[46:47], v[80:81] op_sel_hi:[1,0]
	v_pk_mul_f32 v[80:81], v[48:49], v[80:81] op_sel_hi:[1,0]
	v_pk_mul_f32 v[84:85], v[14:15], v[84:85]
	v_pk_mul_f32 v[80:81], v[16:17], v[80:81]
	v_cvt_pk_bf16_f32 v84, v84, v85
	v_cvt_pk_bf16_f32 v85, v80, v81
	global_store_dwordx2 v[82:83], v[84:85], off offset:1536 nt
	s_add_i32 s7, s27, s34
	s_cmp_gt_i32 s7, 0x100ff
	s_cbranch_scc0 .LBB0_57

.LBB0_62:
	v_pk_mul_f32 v[80:81], v[52:53], v[52:53]
	v_pk_mul_f32 v[82:83], v[50:51], v[50:51]
	s_ashr_i32 s11, s10, 31
	v_pk_mov_b32 v[84:85], v[82:83], v[80:81] op_sel:[1,0]
	v_mov_b32_e32 v83, v81
	v_pk_add_f32 v[80:81], v[84:85], v[82:83]
	v_pk_mul_f32 v[82:83], v[56:57], v[56:57]
	v_pk_add_f32 v[80:81], v[80:81], v[80:81] op_sel_hi:[0,1]
	v_pk_mul_f32 v[84:85], v[54:55], v[54:55]
	v_mul_f32_e32 v80, v58, v58
	v_pk_mov_b32 v[86:87], v[84:85], v[82:83] op_sel:[1,0]
	v_mov_b32_e32 v85, v83
	v_pk_add_f32 v[82:83], v[86:87], v[84:85]
	v_pk_fma_f32 v[84:85], v[58:59], v[58:59], v[80:81] op_sel_hi:[1,1,0]
	v_mul_f32_e32 v80, v60, v60
	v_pk_add_f32 v[82:83], v[82:83], v[82:83] op_sel_hi:[0,1]
	v_pk_fma_f32 v[86:87], v[60:61], v[60:61], v[80:81] op_sel_hi:[1,1,0]
	v_mul_f32_e32 v84, v62, v62
	v_mul_f32_e32 v86, v63, v63
	v_mul_f32_e32 v82, v64, v64
	v_mul_f32_e32 v80, v65, v65
	v_pk_add_f32 v[84:85], v[84:85], v[86:87]
	v_pk_add_f32 v[80:81], v[82:83], v[80:81]
	s_lshl_b64 s[10:11], s[10:11], 11
	v_pk_add_f32 v[80:81], v[84:85], v[80:81]
	v_lshl_add_u64 v[82:83], v[70:71], 0, s[10:11]
	v_add_f32_e32 v79, v80, v81
	ds_bpermute_b32 v80, v67, v79
	s_waitcnt lgkmcnt(0)
	v_add_f32_e32 v79, v79, v80
	ds_bpermute_b32 v80, v74, v79
	s_waitcnt lgkmcnt(0)
	v_add_f32_e32 v79, v79, v80
	ds_bpermute_b32 v80, v75, v79
	s_waitcnt lgkmcnt(0)
	v_add_f32_e32 v79, v79, v80
	ds_bpermute_b32 v80, v76, v79
	s_waitcnt lgkmcnt(0)
	v_add_f32_e32 v79, v79, v80
	ds_bpermute_b32 v80, v77, v79
	s_waitcnt lgkmcnt(0)
	v_add_f32_e32 v79, v79, v80
	ds_bpermute_b32 v80, v78, v79
	s_waitcnt lgkmcnt(0)
	v_add_f32_e32 v79, v79, v80
	v_fmamk_f32 v79, v79, 0x3a800000, v69
	v_rsq_f32_e32 v80, v79
	s_nop 0
	v_pk_mul_f32 v[84:85], v[50:51], v[80:81] op_sel_hi:[1,0]
	v_pk_mul_f32 v[86:87], v[52:53], v[80:81] op_sel_hi:[1,0]
	v_pk_mul_f32 v[88:89], v[54:55], v[80:81] op_sel_hi:[1,0]
	v_pk_mul_f32 v[90:91], v[56:57], v[80:81] op_sel_hi:[1,0]
	v_pk_mul_f32 v[86:87], v[4:5], v[86:87]
	v_pk_mul_f32 v[84:85], v[2:3], v[84:85]
	v_pk_mul_f32 v[90:91], v[8:9], v[90:91]
	v_pk_mul_f32 v[88:89], v[6:7], v[88:89]
	v_cvt_pk_bf16_f32 v84, v84, v85
	v_cvt_pk_bf16_f32 v85, v86, v87
	v_cvt_pk_bf16_f32 v86, v88, v89
	v_cvt_pk_bf16_f32 v87, v90, v91
	global_store_dwordx2 v[82:83], v[84:85], off nt
	global_store_dwordx2 v[82:83], v[86:87], off offset:512 nt
	v_pk_mul_f32 v[84:85], v[58:59], v[80:81] op_sel_hi:[1,0]
	v_pk_mul_f32 v[86:87], v[60:61], v[80:81] op_sel_hi:[1,0]
	v_pk_mul_f32 v[84:85], v[10:11], v[84:85]
	v_pk_mul_f32 v[86:87], v[12:13], v[86:87]
	v_cvt_pk_bf16_f32 v84, v84, v85
	v_cvt_pk_bf16_f32 v85, v86, v87
	global_store_dwordx2 v[82:83], v[84:85], off offset:1024 nt
	v_pk_mul_f32 v[84:85], v[62:63], v[80:81] op_sel_hi:[1,0]
	v_pk_mul_f32 v[80:81], v[64:65], v[80:81] op_sel_hi:[1,0]
	v_pk_mul_f32 v[84:85], v[14:15], v[84:85]
	v_pk_mul_f32 v[80:81], v[16:17], v[80:81]
	v_cvt_pk_bf16_f32 v84, v84, v85
	v_cvt_pk_bf16_f32 v85, v80, v81
	global_store_dwordx2 v[82:83], v[84:85], off offset:1536 nt
	s_add_i32 s7, s29, s34
	s_cmp_gt_i32 s7, 0x100ff
	s_cbranch_scc1 .LBB0_53
